# pool unit: 32 weight-fragment loads issued in two batches of 16 with counted vmcnt instead of serialized load-wait-mfma; on top of mix2/mix1/GEMM changes
# baseline (speedup 1.0000x reference)
.LBB0_149:
	s_or_b64 exec, exec, s[6:7]
	v_readlane_b32 s0, v255, 47
	s_or_b32 s6, s14, s0
	s_ashr_i32 s7, s6, 31
	s_lshl_b64 s[8:9], s[6:7], 15
	v_readlane_b32 s0, v254, 6
	v_bfe_u32 v0, v8, 4, 2
	s_add_u32 s8, s0, s8
	v_readlane_b32 s0, v254, 7
	v_ashrrev_i32_e32 v1, 2, v8
	s_addc_u32 s9, s0, s9
	s_waitcnt vmcnt(0)
	v_and_b32_e32 v32, -16, v1
	v_bfi_b32 v1, -16, v1, v8
	v_lshlrev_b32_e32 v40, 4, v0
	s_movk_i32 s0, 0x110
	v_and_b32_e32 v34, 15, v8
	v_lshlrev_b32_e32 v168, 3, v0
	v_mad_u64_u32 v[0:1], s[10:11], v1, s0, v[40:41]
	v_mov_b32_e32 v41, v169
	v_lshl_add_u64 v[2:3], s[8:9], 0, v[40:41]
	v_lshlrev_b32_e32 v30, 8, v34
	v_mov_b32_e32 v31, v169
	v_lshl_add_u64 v[4:5], v[2:3], 0, v[30:31]
	s_waitcnt lgkmcnt(0)
	s_barrier
	v_mov_b32_e32 v74, v4
	v_mov_b32_e32 v75, v5
	s_mov_b32 s43, 0
	ds_read_b128 v[152:155], v0 offset:21760
	ds_read_b128 v[156:159], v0 offset:21824
	ds_read_b128 v[160:163], v0 offset:21888
	ds_read_b128 v[164:167], v0 offset:21952
	global_load_dwordx4 v[176:179], v[74:75], off
	global_load_dwordx4 v[222:225], v[74:75], off offset:64
	s_mov_b32 s42, 0x1000
	v_lshl_add_u64 v[146:147], v[74:75], 0, s[42:43]
	global_load_dwordx4 v[180:183], v[146:147], off
	global_load_dwordx4 v[226:229], v[146:147], off offset:64
	s_mov_b32 s42, 0x2000
	v_lshl_add_u64 v[146:147], v[74:75], 0, s[42:43]
	global_load_dwordx4 v[184:187], v[146:147], off
	global_load_dwordx4 v[230:233], v[146:147], off offset:64
	s_mov_b32 s42, 0x3000
	v_lshl_add_u64 v[146:147], v[74:75], 0, s[42:43]
	global_load_dwordx4 v[188:191], v[146:147], off
	global_load_dwordx4 v[234:237], v[146:147], off offset:64
	s_mov_b32 s42, 0x4000
	v_lshl_add_u64 v[146:147], v[74:75], 0, s[42:43]
	global_load_dwordx4 v[192:195], v[146:147], off
	global_load_dwordx4 v[238:241], v[146:147], off offset:64
	s_mov_b32 s42, 0x5000
	v_lshl_add_u64 v[146:147], v[74:75], 0, s[42:43]
	global_load_dwordx4 v[196:199], v[146:147], off
	global_load_dwordx4 v[242:245], v[146:147], off offset:64
	s_mov_b32 s42, 0x6000
	v_lshl_add_u64 v[146:147], v[74:75], 0, s[42:43]
	global_load_dwordx4 v[200:203], v[146:147], off
	global_load_dwordx4 v[246:249], v[146:147], off offset:64
	s_mov_b32 s42, 0x7000
	v_lshl_add_u64 v[146:147], v[74:75], 0, s[42:43]
	global_load_dwordx4 v[204:207], v[146:147], off
	global_load_dwordx4 v[148:151], v[146:147], off offset:64
	s_mov_b32 s5, s1
	v_ashrrev_i32_e32 v33, 31, v32
	v_lshl_add_u64 v[32:33], v[32:33], 0, s[4:5]
	s_lshl_b32 s4, s6, 7
	s_ashr_i32 s5, s4, 31
	s_lshl_b64 s[4:5], s[4:5], 2
	s_add_u32 s38, s88, s4
	s_addc_u32 s39, s89, s5
	s_lshl_b32 s0, s14, 9
	v_readlane_b32 s3, v255, 51
	v_readlane_b32 s4, v254, 4
	s_add_u32 s36, s3, s0
	v_readlane_b32 s0, v255, 52
	v_readlane_b32 s5, v254, 5
	v_or_b32_e32 v32, v32, v34
	s_addc_u32 s37, s0, 0
	v_mov_b64_e32 v[34:35], s[4:5]
	s_movk_i32 s0, 0x3020
	v_mad_u64_u32 v[34:35], s[4:5], v32, s0, v[34:35]
	v_mad_i32_i24 v35, v33, s0, v35
	s_lshl_b32 s0, s14, 8
	v_lshlrev_b64 v[32:33], 12, v[32:33]
	v_lshl_add_u64 v[34:35], v[34:35], 0, s[0:1]
	v_lshl_add_u64 v[32:33], s[20:21], 0, v[32:33]
	s_mov_b64 s[4:5], 0x1c20
	s_movk_i32 s3, 0x3020
	s_waitcnt lgkmcnt(0)
	s_waitcnt vmcnt(15)
	v_mfma_f32_16x16x32_f16 v[28:31], v[176:179], v[152:155], 0
	global_load_dwordx4 v[176:179], v[74:75], off offset:128
	s_waitcnt vmcnt(14)
	v_mfma_f32_16x16x32_f16 v[24:27], v[180:183], v[152:155], 0
	s_mov_b32 s42, 0x1000
	v_lshl_add_u64 v[146:147], v[74:75], 0, s[42:43]
	global_load_dwordx4 v[180:183], v[146:147], off offset:128
	s_waitcnt vmcnt(13)
	v_mfma_f32_16x16x32_f16 v[20:23], v[184:187], v[152:155], 0
	s_mov_b32 s42, 0x2000
	v_lshl_add_u64 v[146:147], v[74:75], 0, s[42:43]
	global_load_dwordx4 v[184:187], v[146:147], off offset:128
	s_waitcnt vmcnt(12)
	v_mfma_f32_16x16x32_f16 v[16:19], v[188:191], v[152:155], 0
	s_mov_b32 s42, 0x3000
	v_lshl_add_u64 v[146:147], v[74:75], 0, s[42:43]
	global_load_dwordx4 v[188:191], v[146:147], off offset:128
	s_waitcnt vmcnt(11)
	v_mfma_f32_16x16x32_f16 v[12:15], v[192:195], v[152:155], 0
	s_mov_b32 s42, 0x4000
	v_lshl_add_u64 v[146:147], v[74:75], 0, s[42:43]
	global_load_dwordx4 v[192:195], v[146:147], off offset:128
	s_waitcnt vmcnt(10)
	v_mfma_f32_16x16x32_f16 v[8:11], v[196:199], v[152:155], 0
	s_mov_b32 s42, 0x5000
	v_lshl_add_u64 v[146:147], v[74:75], 0, s[42:43]
	global_load_dwordx4 v[196:199], v[146:147], off offset:128
	s_waitcnt vmcnt(9)
	v_mfma_f32_16x16x32_f16 v[4:7], v[200:203], v[152:155], 0
	s_mov_b32 s42, 0x6000
	v_lshl_add_u64 v[146:147], v[74:75], 0, s[42:43]
	global_load_dwordx4 v[200:203], v[146:147], off offset:128
	s_waitcnt vmcnt(8)
	v_mfma_f32_16x16x32_f16 v[0:3], v[204:207], v[152:155], 0
	s_mov_b32 s42, 0x7000
	v_lshl_add_u64 v[146:147], v[74:75], 0, s[42:43]
	global_load_dwordx4 v[204:207], v[146:147], off offset:128
	s_waitcnt vmcnt(22)
	v_mfma_f32_16x16x32_f16 v[28:31], v[222:225], v[156:159], v[28:31]
	global_load_dwordx4 v[222:225], v[74:75], off offset:192
	s_waitcnt vmcnt(21)
	v_mfma_f32_16x16x32_f16 v[24:27], v[226:229], v[156:159], v[24:27]
	s_mov_b32 s42, 0x1000
	v_lshl_add_u64 v[146:147], v[74:75], 0, s[42:43]
	global_load_dwordx4 v[226:229], v[146:147], off offset:192
	s_waitcnt vmcnt(20)
	v_mfma_f32_16x16x32_f16 v[20:23], v[230:233], v[156:159], v[20:23]
	s_mov_b32 s42, 0x2000
	v_lshl_add_u64 v[146:147], v[74:75], 0, s[42:43]
	global_load_dwordx4 v[230:233], v[146:147], off offset:192
	s_waitcnt vmcnt(19)
	v_mfma_f32_16x16x32_f16 v[16:19], v[234:237], v[156:159], v[16:19]
	s_mov_b32 s42, 0x3000
	v_lshl_add_u64 v[146:147], v[74:75], 0, s[42:43]
	global_load_dwordx4 v[234:237], v[146:147], off offset:192
	s_waitcnt vmcnt(18)
	v_mfma_f32_16x16x32_f16 v[12:15], v[238:241], v[156:159], v[12:15]
	s_mov_b32 s42, 0x4000
	v_lshl_add_u64 v[146:147], v[74:75], 0, s[42:43]
	global_load_dwordx4 v[238:241], v[146:147], off offset:192
	s_waitcnt vmcnt(17)
	v_mfma_f32_16x16x32_f16 v[8:11], v[242:245], v[156:159], v[8:11]
	s_mov_b32 s42, 0x5000
	v_lshl_add_u64 v[146:147], v[74:75], 0, s[42:43]
	global_load_dwordx4 v[242:245], v[146:147], off offset:192
	s_waitcnt vmcnt(16)
	v_mfma_f32_16x16x32_f16 v[4:7], v[246:249], v[156:159], v[4:7]
	s_mov_b32 s42, 0x6000
	v_lshl_add_u64 v[146:147], v[74:75], 0, s[42:43]
	global_load_dwordx4 v[246:249], v[146:147], off offset:192
	s_waitcnt vmcnt(15)
	v_mfma_f32_16x16x32_f16 v[0:3], v[148:151], v[156:159], v[0:3]
	s_mov_b32 s42, 0x7000
	v_lshl_add_u64 v[146:147], v[74:75], 0, s[42:43]
	global_load_dwordx4 v[148:151], v[146:147], off offset:192
	s_waitcnt vmcnt(15)
	v_mfma_f32_16x16x32_f16 v[28:31], v[176:179], v[160:163], v[28:31]
	s_waitcnt vmcnt(14)
	v_mfma_f32_16x16x32_f16 v[24:27], v[180:183], v[160:163], v[24:27]
	s_waitcnt vmcnt(13)
	v_mfma_f32_16x16x32_f16 v[20:23], v[184:187], v[160:163], v[20:23]
	s_waitcnt vmcnt(12)
	v_mfma_f32_16x16x32_f16 v[16:19], v[188:191], v[160:163], v[16:19]
	s_waitcnt vmcnt(11)
	v_mfma_f32_16x16x32_f16 v[12:15], v[192:195], v[160:163], v[12:15]
	s_waitcnt vmcnt(10)
	v_mfma_f32_16x16x32_f16 v[8:11], v[196:199], v[160:163], v[8:11]
	s_waitcnt vmcnt(9)
	v_mfma_f32_16x16x32_f16 v[4:7], v[200:203], v[160:163], v[4:7]
	s_waitcnt vmcnt(8)
	v_mfma_f32_16x16x32_f16 v[0:3], v[204:207], v[160:163], v[0:3]
	s_waitcnt vmcnt(7)
	v_mfma_f32_16x16x32_f16 v[28:31], v[222:225], v[164:167], v[28:31]
	s_waitcnt vmcnt(6)
	v_mfma_f32_16x16x32_f16 v[24:27], v[226:229], v[164:167], v[24:27]
	s_waitcnt vmcnt(5)
	v_mfma_f32_16x16x32_f16 v[20:23], v[230:233], v[164:167], v[20:23]
	s_waitcnt vmcnt(4)
	v_mfma_f32_16x16x32_f16 v[16:19], v[234:237], v[164:167], v[16:19]
	s_waitcnt vmcnt(3)
	v_mfma_f32_16x16x32_f16 v[12:15], v[238:241], v[164:167], v[12:15]
	s_waitcnt vmcnt(2)
	v_mfma_f32_16x16x32_f16 v[8:11], v[242:245], v[164:167], v[8:11]
	s_waitcnt vmcnt(1)
	v_mfma_f32_16x16x32_f16 v[4:7], v[246:249], v[164:167], v[4:7]
	s_waitcnt vmcnt(0)
	v_mfma_f32_16x16x32_f16 v[0:3], v[148:151], v[164:167], v[0:3]
	v_lshl_add_u64 v[44:45], v[32:33], 0, s[0:1]
	v_lshl_add_u64 v[32:33], v[34:35], 0, v[168:169]
	s_movk_i32 s0, 0x1000
	v_lshl_add_u64 v[42:43], v[32:33], 0, s[4:5]
	v_add_co_u32_e32 v32, vcc, s0, v32
	s_mov_b32 s0, 0x47ff000
	s_nop 0
	v_addc_co_u32_e32 v33, vcc, 0, v33, vcc
	s_mov_b64 s[8:9], 0xc0
	s_nop 7
	global_load_dwordx2 v[46:47], v[32:33], off offset:3104
	global_load_dwordx4 v[32:35], v40, s[38:39]
	global_load_dwordx4 v[36:39], v40, s[36:37]
	global_load_dwordx2 v[132:133], v[42:43], off offset:32
	global_load_dwordx4 v[76:79], v40, s[38:39] offset:64
	global_load_dwordx4 v[80:83], v40, s[36:37] offset:64
	global_load_dwordx2 v[134:135], v[42:43], off offset:64
	global_load_dwordx4 v[84:87], v40, s[38:39] offset:128
	global_load_dwordx4 v[88:91], v40, s[36:37] offset:128
	global_load_dwordx2 v[136:137], v[42:43], off offset:96
	global_load_dwordx4 v[92:95], v40, s[38:39] offset:192
	global_load_dwordx4 v[96:99], v40, s[36:37] offset:192
	global_load_dwordx2 v[138:139], v[42:43], off offset:128
	global_load_dwordx4 v[100:103], v40, s[38:39] offset:256
	global_load_dwordx4 v[104:107], v40, s[36:37] offset:256
	global_load_dwordx2 v[140:141], v[42:43], off offset:160
	global_load_dwordx4 v[108:111], v40, s[38:39] offset:320
	global_load_dwordx4 v[112:115], v40, s[36:37] offset:320
	global_load_dwordx2 v[142:143], v[42:43], off offset:192
	global_load_dwordx4 v[116:119], v40, s[38:39] offset:384
	global_load_dwordx4 v[120:123], v40, s[36:37] offset:384
	global_load_dwordx2 v[144:145], v[42:43], off offset:224
	global_load_dwordx4 v[124:127], v40, s[38:39] offset:448
	global_load_dwordx4 v[128:131], v40, s[36:37] offset:448
	s_waitcnt vmcnt(23)
	v_cvt_f32_f16_sdwa v41, v46 dst_sel:DWORD dst_unused:UNUSED_PAD src0_sel:WORD_1
	v_cvt_f32_f16_e32 v46, v46
	s_waitcnt vmcnt(22)
	v_pk_add_f32 v[28:29], v[28:29], v[32:33]
	v_pk_add_f32 v[30:31], v[30:31], v[34:35]
	v_mul_f32_e32 v32, 0xbfb8aa3b, v41
	v_mul_f32_e32 v48, 0xbfb8aa3b, v46
	v_exp_f32_e32 v48, v48
	v_exp_f32_e32 v49, v32
	s_waitcnt vmcnt(21)
	v_pk_mul_f32 v[28:29], v[28:29], v[36:37]
	v_pk_mul_f32 v[30:31], v[30:31], v[38:39]
	v_pk_add_f32 v[32:33], v[48:49], 1.0 op_sel_hi:[1,0]
	s_nop 0
	v_div_scale_f32 v36, s[4:5], v33, v33, v41
	v_rcp_f32_e32 v37, v36
	s_nop 0
	v_fma_f32 v48, -v36, v37, 1.0
	v_fmac_f32_e32 v37, v48, v37
	v_div_scale_f32 v48, vcc, v41, v33, v41
	v_mul_f32_e32 v49, v48, v37
	v_fma_f32 v50, -v36, v49, v48
	v_fmac_f32_e32 v49, v50, v37
	v_fma_f32 v36, -v36, v49, v48
	v_div_fmas_f32 v36, v36, v37, v49
	v_div_fixup_f32 v33, v36, v33, v41
	v_div_scale_f32 v36, s[4:5], v32, v32, v46
	v_rcp_f32_e32 v37, v36
	s_nop 0
	v_fma_f32 v41, -v36, v37, 1.0
	v_fmac_f32_e32 v37, v41, v37
	v_div_scale_f32 v41, vcc, v46, v32, v46
	v_mul_f32_e32 v48, v41, v37
	v_fma_f32 v49, -v36, v48, v41
	v_fmac_f32_e32 v48, v49, v37
	v_fma_f32 v36, -v36, v48, v41
	v_div_fmas_f32 v36, v36, v37, v48
	v_div_fixup_f32 v32, v36, v32, v46
	v_pk_mul_f32 v[28:29], v[28:29], v[32:33]
	v_cvt_f32_f16_sdwa v33, v47 dst_sel:DWORD dst_unused:UNUSED_PAD src0_sel:WORD_1
	v_cvt_f32_f16_e32 v36, v47
	v_cvt_pk_f16_f32 v32, v28, v29
	v_mul_f32_e32 v29, 0xbfb8aa3b, v33
	v_mul_f32_e32 v28, 0xbfb8aa3b, v36
	v_exp_f32_e32 v28, v28
	v_exp_f32_e32 v29, v29
	s_nop 0
	v_pk_add_f32 v[28:29], v[28:29], 1.0 op_sel_hi:[1,0]
	s_nop 0
	v_div_scale_f32 v34, s[4:5], v29, v29, v33
	v_rcp_f32_e32 v35, v34
	s_nop 0
	v_fma_f32 v37, -v34, v35, 1.0
	v_fmac_f32_e32 v35, v37, v35
	v_div_scale_f32 v37, vcc, v33, v29, v33
	v_mul_f32_e32 v38, v37, v35
	v_fma_f32 v39, -v34, v38, v37
	v_fmac_f32_e32 v38, v39, v35
	v_fma_f32 v34, -v34, v38, v37
	v_div_fmas_f32 v34, v34, v35, v38
	v_div_fixup_f32 v29, v34, v29, v33
	v_div_scale_f32 v33, s[4:5], v28, v28, v36
	v_rcp_f32_e32 v34, v33
	s_mov_b64 s[4:5], 0x47fff00
	v_fma_f32 v35, -v33, v34, 1.0
	v_fmac_f32_e32 v34, v35, v34
	v_div_scale_f32 v35, vcc, v36, v28, v36
	v_mul_f32_e32 v37, v35, v34
	v_fma_f32 v38, -v33, v37, v35
	v_fmac_f32_e32 v37, v38, v34
	v_fma_f32 v33, -v33, v37, v35
	v_div_fmas_f32 v33, v33, v34, v37
	v_div_fixup_f32 v28, v33, v28, v36
	v_pk_mul_f32 v[28:29], v[30:31], v[28:29]
	v_lshl_add_u64 v[30:31], v[44:45], 0, v[168:169]
	v_cvt_pk_f16_f32 v33, v28, v29
	v_lshl_add_u64 v[28:29], v[30:31], 0, s[4:5]
	v_add_co_u32_e32 v30, vcc, s0, v30
	s_nop 1
	v_addc_co_u32_e32 v31, vcc, 0, v31, vcc
	global_store_dwordx2 v[30:31], v[32:33], off offset:3840
	s_nop 0
	s_waitcnt vmcnt(21)
	v_cvt_f32_f16_sdwa v41, v132 dst_sel:DWORD dst_unused:UNUSED_PAD src0_sel:WORD_1
	v_cvt_f32_f16_e32 v38, v132
	s_waitcnt vmcnt(20)
	v_pk_add_f32 v[24:25], v[24:25], v[76:77]
	v_pk_add_f32 v[26:27], v[26:27], v[78:79]
	v_mul_f32_e32 v30, 0xbfb8aa3b, v41
	v_mul_f32_e32 v44, 0xbfb8aa3b, v38
	v_exp_f32_e32 v44, v44
	v_exp_f32_e32 v45, v30
	s_waitcnt vmcnt(19)
	v_pk_mul_f32 v[24:25], v[24:25], v[80:81]
	v_pk_mul_f32 v[26:27], v[26:27], v[82:83]
	v_pk_add_f32 v[30:31], v[44:45], 1.0 op_sel_hi:[1,0]
	s_nop 0
	v_div_scale_f32 v34, s[4:5], v31, v31, v41
	v_rcp_f32_e32 v35, v34
	s_nop 0
	v_fma_f32 v44, -v34, v35, 1.0
	v_fmac_f32_e32 v35, v44, v35
	v_div_scale_f32 v44, vcc, v41, v31, v41
	v_mul_f32_e32 v45, v44, v35
	v_fma_f32 v46, -v34, v45, v44
	v_fmac_f32_e32 v45, v46, v35
	v_fma_f32 v34, -v34, v45, v44
	v_div_fmas_f32 v34, v34, v35, v45
	v_div_fixup_f32 v31, v34, v31, v41
	v_div_scale_f32 v34, s[4:5], v30, v30, v38
	v_rcp_f32_e32 v35, v34
	s_nop 0
	v_fma_f32 v41, -v34, v35, 1.0
	v_fmac_f32_e32 v35, v41, v35
	v_div_scale_f32 v41, vcc, v38, v30, v38
	v_mul_f32_e32 v44, v41, v35
	v_fma_f32 v45, -v34, v44, v41
	v_fmac_f32_e32 v44, v45, v35
	v_fma_f32 v34, -v34, v44, v41
	v_div_fmas_f32 v34, v34, v35, v44
	v_div_fixup_f32 v30, v34, v30, v38
	v_pk_mul_f32 v[24:25], v[24:25], v[30:31]
	v_cvt_f32_f16_e32 v34, v133
	v_cvt_pk_f16_f32 v24, v24, v25
	v_cvt_f32_f16_sdwa v25, v133 dst_sel:DWORD dst_unused:UNUSED_PAD src0_sel:WORD_1
	v_mul_f32_e32 v30, 0xbfb8aa3b, v34
	v_exp_f32_e32 v30, v30
	v_mul_f32_e32 v31, 0xbfb8aa3b, v25
	v_exp_f32_e32 v31, v31
	s_nop 0
	v_pk_add_f32 v[30:31], v[30:31], 1.0 op_sel_hi:[1,0]
	s_nop 0
	v_div_scale_f32 v32, s[4:5], v31, v31, v25
	v_rcp_f32_e32 v33, v32
	s_nop 0
	v_fma_f32 v35, -v32, v33, 1.0
	v_fmac_f32_e32 v33, v35, v33
	v_div_scale_f32 v35, vcc, v25, v31, v25
	v_mul_f32_e32 v36, v35, v33
	v_fma_f32 v37, -v32, v36, v35
	v_fmac_f32_e32 v36, v37, v33
	v_fma_f32 v32, -v32, v36, v35
	v_div_fmas_f32 v32, v32, v33, v36
	v_div_fixup_f32 v31, v32, v31, v25
	v_div_scale_f32 v25, s[4:5], v30, v30, v34
	v_rcp_f32_e32 v32, v25
	s_nop 0
	v_fma_f32 v33, -v25, v32, 1.0
	v_fmac_f32_e32 v32, v33, v32
	v_div_scale_f32 v33, vcc, v34, v30, v34
	v_mul_f32_e32 v35, v33, v32
	v_fma_f32 v36, -v25, v35, v33
	v_fmac_f32_e32 v35, v36, v32
	v_fma_f32 v25, -v25, v35, v33
	v_div_fmas_f32 v25, v25, v32, v35
	v_div_fixup_f32 v30, v25, v30, v34
	v_pk_mul_f32 v[26:27], v[26:27], v[30:31]
	s_nop 0
	v_cvt_pk_f16_f32 v25, v26, v27
	global_store_dwordx2 v[28:29], v[24:25], off offset:32
	s_nop 0
	s_waitcnt vmcnt(19)
	v_cvt_f32_f16_sdwa v38, v134 dst_sel:DWORD dst_unused:UNUSED_PAD src0_sel:WORD_1
	v_cvt_f32_f16_e32 v34, v134
	s_waitcnt vmcnt(18)
	v_pk_add_f32 v[20:21], v[20:21], v[84:85]
	v_pk_add_f32 v[22:23], v[22:23], v[86:87]
	v_mul_f32_e32 v24, 0xbfb8aa3b, v38
	v_mul_f32_e32 v36, 0xbfb8aa3b, v34
	v_exp_f32_e32 v36, v36
	v_exp_f32_e32 v37, v24
	s_waitcnt vmcnt(17)
	v_pk_mul_f32 v[20:21], v[20:21], v[88:89]
	v_pk_mul_f32 v[22:23], v[22:23], v[90:91]
	v_pk_add_f32 v[24:25], v[36:37], 1.0 op_sel_hi:[1,0]
	s_nop 0
	v_div_scale_f32 v30, s[4:5], v25, v25, v38
	v_rcp_f32_e32 v31, v30
	s_nop 0
	v_fma_f32 v36, -v30, v31, 1.0
	v_fmac_f32_e32 v31, v36, v31
	v_div_scale_f32 v36, vcc, v38, v25, v38
	v_mul_f32_e32 v37, v36, v31
	v_fma_f32 v39, -v30, v37, v36
	v_fmac_f32_e32 v37, v39, v31
	v_fma_f32 v30, -v30, v37, v36
	v_div_fmas_f32 v30, v30, v31, v37
	v_div_fixup_f32 v25, v30, v25, v38
	v_div_scale_f32 v30, s[4:5], v24, v24, v34
	v_rcp_f32_e32 v31, v30
	s_nop 0
	v_fma_f32 v36, -v30, v31, 1.0
	v_fmac_f32_e32 v31, v36, v31
	v_div_scale_f32 v36, vcc, v34, v24, v34
	v_mul_f32_e32 v37, v36, v31
	v_fma_f32 v38, -v30, v37, v36
	v_fmac_f32_e32 v37, v38, v31
	v_fma_f32 v30, -v30, v37, v36
	v_div_fmas_f32 v30, v30, v31, v37
	v_div_fixup_f32 v24, v30, v24, v34
	v_pk_mul_f32 v[20:21], v[20:21], v[24:25]
	v_cvt_f32_f16_e32 v30, v135
	v_cvt_pk_f16_f32 v20, v20, v21
	v_cvt_f32_f16_sdwa v21, v135 dst_sel:DWORD dst_unused:UNUSED_PAD src0_sel:WORD_1
	v_mul_f32_e32 v24, 0xbfb8aa3b, v30
	v_exp_f32_e32 v24, v24
	v_mul_f32_e32 v25, 0xbfb8aa3b, v21
	v_exp_f32_e32 v25, v25
	s_nop 0
	v_pk_add_f32 v[24:25], v[24:25], 1.0 op_sel_hi:[1,0]
	s_nop 0
	v_div_scale_f32 v26, s[4:5], v25, v25, v21
	v_rcp_f32_e32 v27, v26
	s_nop 0
	v_fma_f32 v31, -v26, v27, 1.0
	v_fmac_f32_e32 v27, v31, v27
	v_div_scale_f32 v31, vcc, v21, v25, v21
	v_mul_f32_e32 v32, v31, v27
	v_fma_f32 v33, -v26, v32, v31
	v_fmac_f32_e32 v32, v33, v27
	v_fma_f32 v26, -v26, v32, v31
	v_div_fmas_f32 v26, v26, v27, v32
	v_div_fixup_f32 v25, v26, v25, v21
	v_div_scale_f32 v21, s[4:5], v24, v24, v30
	v_rcp_f32_e32 v26, v21
	s_nop 0
	v_fma_f32 v27, -v21, v26, 1.0
	v_fmac_f32_e32 v26, v27, v26
	v_div_scale_f32 v27, vcc, v30, v24, v30
	v_mul_f32_e32 v31, v27, v26
	v_fma_f32 v32, -v21, v31, v27
	v_fmac_f32_e32 v31, v32, v26
	v_fma_f32 v21, -v21, v31, v27
	v_div_fmas_f32 v21, v21, v26, v31
	v_div_fixup_f32 v24, v21, v24, v30
	v_pk_mul_f32 v[22:23], v[22:23], v[24:25]
	s_nop 0
	v_cvt_pk_f16_f32 v21, v22, v23
	global_store_dwordx2 v[28:29], v[20:21], off offset:64
	s_nop 0
	s_waitcnt vmcnt(17)
	v_cvt_f32_f16_sdwa v34, v136 dst_sel:DWORD dst_unused:UNUSED_PAD src0_sel:WORD_1
	v_cvt_f32_f16_e32 v30, v136
	s_waitcnt vmcnt(16)
	v_pk_add_f32 v[16:17], v[16:17], v[92:93]
	v_pk_add_f32 v[18:19], v[18:19], v[94:95]
	v_mul_f32_e32 v20, 0xbfb8aa3b, v34
	v_mul_f32_e32 v32, 0xbfb8aa3b, v30
	v_exp_f32_e32 v32, v32
	v_exp_f32_e32 v33, v20
	s_waitcnt vmcnt(15)
	v_pk_mul_f32 v[16:17], v[16:17], v[96:97]
	v_pk_mul_f32 v[18:19], v[18:19], v[98:99]
	v_pk_add_f32 v[20:21], v[32:33], 1.0 op_sel_hi:[1,0]
	s_nop 0
	v_div_scale_f32 v24, s[4:5], v21, v21, v34
	v_rcp_f32_e32 v25, v24
	s_nop 0
	v_fma_f32 v32, -v24, v25, 1.0
	v_fmac_f32_e32 v25, v32, v25
	v_div_scale_f32 v32, vcc, v34, v21, v34
	v_mul_f32_e32 v33, v32, v25
	v_fma_f32 v35, -v24, v33, v32
	v_fmac_f32_e32 v33, v35, v25
	v_fma_f32 v24, -v24, v33, v32
	v_div_fmas_f32 v24, v24, v25, v33
	v_div_fixup_f32 v21, v24, v21, v34
	v_div_scale_f32 v24, s[4:5], v20, v20, v30
	v_rcp_f32_e32 v25, v24
	s_nop 0
	v_fma_f32 v32, -v24, v25, 1.0
	v_fmac_f32_e32 v25, v32, v25
	v_div_scale_f32 v32, vcc, v30, v20, v30
	v_mul_f32_e32 v33, v32, v25
	v_fma_f32 v34, -v24, v33, v32
	v_fmac_f32_e32 v33, v34, v25
	v_fma_f32 v24, -v24, v33, v32
	v_div_fmas_f32 v24, v24, v25, v33
	v_div_fixup_f32 v20, v24, v20, v30
	v_pk_mul_f32 v[16:17], v[16:17], v[20:21]
	v_cvt_f32_f16_e32 v24, v137
	v_cvt_pk_f16_f32 v16, v16, v17
	v_cvt_f32_f16_sdwa v17, v137 dst_sel:DWORD dst_unused:UNUSED_PAD src0_sel:WORD_1
	v_mul_f32_e32 v20, 0xbfb8aa3b, v24
	v_exp_f32_e32 v20, v20
	v_mul_f32_e32 v21, 0xbfb8aa3b, v17
	v_exp_f32_e32 v21, v21
	s_nop 0
	v_pk_add_f32 v[20:21], v[20:21], 1.0 op_sel_hi:[1,0]
	s_nop 0
	v_div_scale_f32 v22, s[4:5], v21, v21, v17
	v_rcp_f32_e32 v23, v22
	s_nop 0
	v_fma_f32 v25, -v22, v23, 1.0
	v_fmac_f32_e32 v23, v25, v23
	v_div_scale_f32 v25, vcc, v17, v21, v17
	v_mul_f32_e32 v26, v25, v23
	v_fma_f32 v27, -v22, v26, v25
	v_fmac_f32_e32 v26, v27, v23
	v_fma_f32 v22, -v22, v26, v25
	v_div_fmas_f32 v22, v22, v23, v26
	v_div_fixup_f32 v21, v22, v21, v17
	v_div_scale_f32 v17, s[4:5], v20, v20, v24
	v_rcp_f32_e32 v22, v17
	s_nop 0
	v_fma_f32 v23, -v17, v22, 1.0
	v_fmac_f32_e32 v22, v23, v22
	v_div_scale_f32 v23, vcc, v24, v20, v24
	v_mul_f32_e32 v25, v23, v22
	v_fma_f32 v26, -v17, v25, v23
	v_fmac_f32_e32 v25, v26, v22
	v_fma_f32 v17, -v17, v25, v23
	v_div_fmas_f32 v17, v17, v22, v25
	v_div_fixup_f32 v20, v17, v20, v24
	v_pk_mul_f32 v[18:19], v[18:19], v[20:21]
	s_nop 0
	v_cvt_pk_f16_f32 v17, v18, v19
	global_store_dwordx2 v[28:29], v[16:17], off offset:96
	s_nop 0
	s_waitcnt vmcnt(15)
	v_cvt_f32_f16_sdwa v30, v138 dst_sel:DWORD dst_unused:UNUSED_PAD src0_sel:WORD_1
	v_cvt_f32_f16_e32 v24, v138
	s_waitcnt vmcnt(14)
	v_pk_add_f32 v[12:13], v[12:13], v[100:101]
	v_pk_add_f32 v[14:15], v[14:15], v[102:103]
	v_mul_f32_e32 v16, 0xbfb8aa3b, v30
	v_mul_f32_e32 v26, 0xbfb8aa3b, v24
	v_exp_f32_e32 v26, v26
	v_exp_f32_e32 v27, v16
	s_waitcnt vmcnt(13)
	v_pk_mul_f32 v[12:13], v[12:13], v[104:105]
	v_pk_mul_f32 v[14:15], v[14:15], v[106:107]
	v_pk_add_f32 v[16:17], v[26:27], 1.0 op_sel_hi:[1,0]
	s_nop 0
	v_div_scale_f32 v20, s[4:5], v17, v17, v30
	v_rcp_f32_e32 v21, v20
	s_nop 0
	v_fma_f32 v26, -v20, v21, 1.0
	v_fmac_f32_e32 v21, v26, v21
	v_div_scale_f32 v26, vcc, v30, v17, v30
	v_mul_f32_e32 v27, v26, v21
	v_fma_f32 v31, -v20, v27, v26
	v_fmac_f32_e32 v27, v31, v21
	v_fma_f32 v20, -v20, v27, v26
	v_div_fmas_f32 v20, v20, v21, v27
	v_div_fixup_f32 v17, v20, v17, v30
	v_div_scale_f32 v20, s[4:5], v16, v16, v24
	v_rcp_f32_e32 v21, v20
	s_nop 0
	v_fma_f32 v26, -v20, v21, 1.0
	v_fmac_f32_e32 v21, v26, v21
	v_div_scale_f32 v26, vcc, v24, v16, v24
	v_mul_f32_e32 v27, v26, v21
	v_fma_f32 v30, -v20, v27, v26
	v_fmac_f32_e32 v27, v30, v21
	v_fma_f32 v20, -v20, v27, v26
	v_div_fmas_f32 v20, v20, v21, v27
	v_div_fixup_f32 v16, v20, v16, v24
	v_pk_mul_f32 v[12:13], v[12:13], v[16:17]
	v_cvt_f32_f16_e32 v20, v139
	v_cvt_pk_f16_f32 v12, v12, v13
	v_cvt_f32_f16_sdwa v13, v139 dst_sel:DWORD dst_unused:UNUSED_PAD src0_sel:WORD_1
	v_mul_f32_e32 v16, 0xbfb8aa3b, v20
	v_exp_f32_e32 v16, v16
	v_mul_f32_e32 v17, 0xbfb8aa3b, v13
	v_exp_f32_e32 v17, v17
	s_nop 0
	v_pk_add_f32 v[16:17], v[16:17], 1.0 op_sel_hi:[1,0]
	s_nop 0
	v_div_scale_f32 v18, s[4:5], v17, v17, v13
	v_rcp_f32_e32 v19, v18
	s_nop 0
	v_fma_f32 v21, -v18, v19, 1.0
	v_fmac_f32_e32 v19, v21, v19
	v_div_scale_f32 v21, vcc, v13, v17, v13
	v_mul_f32_e32 v22, v21, v19
	v_fma_f32 v23, -v18, v22, v21
	v_fmac_f32_e32 v22, v23, v19
	v_fma_f32 v18, -v18, v22, v21
	v_div_fmas_f32 v18, v18, v19, v22
	v_div_fixup_f32 v17, v18, v17, v13
	v_div_scale_f32 v13, s[4:5], v16, v16, v20
	v_rcp_f32_e32 v18, v13
	s_nop 0
	v_fma_f32 v19, -v13, v18, 1.0
	v_fmac_f32_e32 v18, v19, v18
	v_div_scale_f32 v19, vcc, v20, v16, v20
	v_mul_f32_e32 v21, v19, v18
	v_fma_f32 v22, -v13, v21, v19
	v_fmac_f32_e32 v21, v22, v18
	v_fma_f32 v13, -v13, v21, v19
	v_div_fmas_f32 v13, v13, v18, v21
	v_div_fixup_f32 v16, v13, v16, v20
	v_pk_mul_f32 v[14:15], v[14:15], v[16:17]
	s_nop 0
	v_cvt_pk_f16_f32 v13, v14, v15
	global_store_dwordx2 v[28:29], v[12:13], off offset:128
	s_nop 0
	s_waitcnt vmcnt(13)
	v_cvt_f32_f16_sdwa v24, v140 dst_sel:DWORD dst_unused:UNUSED_PAD src0_sel:WORD_1
	v_cvt_f32_f16_e32 v20, v140
	s_waitcnt vmcnt(12)
	v_pk_add_f32 v[8:9], v[8:9], v[108:109]
	v_pk_add_f32 v[10:11], v[10:11], v[110:111]
	v_mul_f32_e32 v12, 0xbfb8aa3b, v24
	v_mul_f32_e32 v22, 0xbfb8aa3b, v20
	v_exp_f32_e32 v22, v22
	v_exp_f32_e32 v23, v12
	s_waitcnt vmcnt(11)
	v_pk_mul_f32 v[8:9], v[8:9], v[112:113]
	v_pk_mul_f32 v[10:11], v[10:11], v[114:115]
	v_pk_add_f32 v[12:13], v[22:23], 1.0 op_sel_hi:[1,0]
	s_nop 0
	v_div_scale_f32 v16, s[4:5], v13, v13, v24
	v_rcp_f32_e32 v17, v16
	s_nop 0
	v_fma_f32 v22, -v16, v17, 1.0
	v_fmac_f32_e32 v17, v22, v17
	v_div_scale_f32 v22, vcc, v24, v13, v24
	v_mul_f32_e32 v23, v22, v17
	v_fma_f32 v25, -v16, v23, v22
	v_fmac_f32_e32 v23, v25, v17
	v_fma_f32 v16, -v16, v23, v22
	v_div_fmas_f32 v16, v16, v17, v23
	v_div_fixup_f32 v13, v16, v13, v24
	v_div_scale_f32 v16, s[4:5], v12, v12, v20
	v_rcp_f32_e32 v17, v16
	s_nop 0
	v_fma_f32 v22, -v16, v17, 1.0
	v_fmac_f32_e32 v17, v22, v17
	v_div_scale_f32 v22, vcc, v20, v12, v20
	v_mul_f32_e32 v23, v22, v17
	v_fma_f32 v24, -v16, v23, v22
	v_fmac_f32_e32 v23, v24, v17
	v_fma_f32 v16, -v16, v23, v22
	v_div_fmas_f32 v16, v16, v17, v23
	v_div_fixup_f32 v12, v16, v12, v20
	v_pk_mul_f32 v[8:9], v[8:9], v[12:13]
	v_cvt_f32_f16_e32 v16, v141
	v_cvt_pk_f16_f32 v8, v8, v9
	v_cvt_f32_f16_sdwa v9, v141 dst_sel:DWORD dst_unused:UNUSED_PAD src0_sel:WORD_1
	v_mul_f32_e32 v12, 0xbfb8aa3b, v16
	v_exp_f32_e32 v12, v12
	v_mul_f32_e32 v13, 0xbfb8aa3b, v9
	v_exp_f32_e32 v13, v13
	s_nop 0
	v_pk_add_f32 v[12:13], v[12:13], 1.0 op_sel_hi:[1,0]
	s_nop 0
	v_div_scale_f32 v14, s[4:5], v13, v13, v9
	v_rcp_f32_e32 v15, v14
	s_nop 0
	v_fma_f32 v17, -v14, v15, 1.0
	v_fmac_f32_e32 v15, v17, v15
	v_div_scale_f32 v17, vcc, v9, v13, v9
	v_mul_f32_e32 v18, v17, v15
	v_fma_f32 v19, -v14, v18, v17
	v_fmac_f32_e32 v18, v19, v15
	v_fma_f32 v14, -v14, v18, v17
	v_div_fmas_f32 v14, v14, v15, v18
	v_div_fixup_f32 v13, v14, v13, v9
	v_div_scale_f32 v9, s[4:5], v12, v12, v16
	v_rcp_f32_e32 v14, v9
	s_nop 0
	v_fma_f32 v15, -v9, v14, 1.0
	v_fmac_f32_e32 v14, v15, v14
	v_div_scale_f32 v15, vcc, v16, v12, v16
	v_mul_f32_e32 v17, v15, v14
	v_fma_f32 v18, -v9, v17, v15
	v_fmac_f32_e32 v17, v18, v14
	v_fma_f32 v9, -v9, v17, v15
	v_div_fmas_f32 v9, v9, v14, v17
	v_div_fixup_f32 v12, v9, v12, v16
	v_pk_mul_f32 v[10:11], v[10:11], v[12:13]
	s_nop 0
	v_cvt_pk_f16_f32 v9, v10, v11
	global_store_dwordx2 v[28:29], v[8:9], off offset:160
	s_nop 0
	s_waitcnt vmcnt(11)
	v_cvt_f32_f16_sdwa v20, v142 dst_sel:DWORD dst_unused:UNUSED_PAD src0_sel:WORD_1
	v_cvt_f32_f16_e32 v16, v142
	s_waitcnt vmcnt(10)
	v_pk_add_f32 v[4:5], v[4:5], v[116:117]
	v_pk_add_f32 v[6:7], v[6:7], v[118:119]
	v_mul_f32_e32 v8, 0xbfb8aa3b, v20
	v_mul_f32_e32 v18, 0xbfb8aa3b, v16
	v_exp_f32_e32 v18, v18
	v_exp_f32_e32 v19, v8
	s_waitcnt vmcnt(9)
	v_pk_mul_f32 v[4:5], v[4:5], v[120:121]
	v_pk_mul_f32 v[6:7], v[6:7], v[122:123]
	v_pk_add_f32 v[8:9], v[18:19], 1.0 op_sel_hi:[1,0]
	s_nop 0
	v_div_scale_f32 v12, s[4:5], v9, v9, v20
	v_rcp_f32_e32 v13, v12
	s_nop 0
	v_fma_f32 v18, -v12, v13, 1.0
	v_fmac_f32_e32 v13, v18, v13
	v_div_scale_f32 v18, vcc, v20, v9, v20
	v_mul_f32_e32 v19, v18, v13
	v_fma_f32 v21, -v12, v19, v18
	v_fmac_f32_e32 v19, v21, v13
	v_fma_f32 v12, -v12, v19, v18
	v_div_fmas_f32 v12, v12, v13, v19
	v_div_fixup_f32 v9, v12, v9, v20
	v_div_scale_f32 v12, s[4:5], v8, v8, v16
	v_rcp_f32_e32 v13, v12
	s_nop 0
	v_fma_f32 v18, -v12, v13, 1.0
	v_fmac_f32_e32 v13, v18, v13
	v_div_scale_f32 v18, vcc, v16, v8, v16
	v_mul_f32_e32 v19, v18, v13
	v_fma_f32 v20, -v12, v19, v18
	v_fmac_f32_e32 v19, v20, v13
	v_fma_f32 v12, -v12, v19, v18
	v_div_fmas_f32 v12, v12, v13, v19
	v_div_fixup_f32 v8, v12, v8, v16
	v_pk_mul_f32 v[4:5], v[4:5], v[8:9]
	v_cvt_f32_f16_e32 v12, v143
	v_cvt_pk_f16_f32 v4, v4, v5
	v_cvt_f32_f16_sdwa v5, v143 dst_sel:DWORD dst_unused:UNUSED_PAD src0_sel:WORD_1
	v_mul_f32_e32 v8, 0xbfb8aa3b, v12
	v_exp_f32_e32 v8, v8
	v_mul_f32_e32 v9, 0xbfb8aa3b, v5
	v_exp_f32_e32 v9, v9
	s_nop 0
	v_pk_add_f32 v[8:9], v[8:9], 1.0 op_sel_hi:[1,0]
	s_nop 0
	v_div_scale_f32 v10, s[4:5], v9, v9, v5
	v_rcp_f32_e32 v11, v10
	s_nop 0
	v_fma_f32 v13, -v10, v11, 1.0
	v_fmac_f32_e32 v11, v13, v11
	v_div_scale_f32 v13, vcc, v5, v9, v5
	v_mul_f32_e32 v14, v13, v11
	v_fma_f32 v15, -v10, v14, v13
	v_fmac_f32_e32 v14, v15, v11
	v_fma_f32 v10, -v10, v14, v13
	v_div_fmas_f32 v10, v10, v11, v14
	v_div_fixup_f32 v9, v10, v9, v5
	v_div_scale_f32 v5, s[4:5], v8, v8, v12
	v_rcp_f32_e32 v10, v5
	s_nop 0
	v_fma_f32 v11, -v5, v10, 1.0
	v_fmac_f32_e32 v10, v11, v10
	v_div_scale_f32 v11, vcc, v12, v8, v12
	v_mul_f32_e32 v13, v11, v10
	v_fma_f32 v14, -v5, v13, v11
	v_fmac_f32_e32 v13, v14, v10
	v_fma_f32 v5, -v5, v13, v11
	v_div_fmas_f32 v5, v5, v10, v13
	v_div_fixup_f32 v8, v5, v8, v12
	v_pk_mul_f32 v[6:7], v[6:7], v[8:9]
	s_nop 0
	v_cvt_pk_f16_f32 v5, v6, v7
	global_store_dwordx2 v[28:29], v[4:5], off offset:192
	s_nop 0
	s_waitcnt vmcnt(9)
	v_cvt_f32_f16_sdwa v16, v144 dst_sel:DWORD dst_unused:UNUSED_PAD src0_sel:WORD_1
	v_cvt_f32_f16_e32 v12, v144
	s_waitcnt vmcnt(8)
	v_pk_add_f32 v[0:1], v[0:1], v[124:125]
	v_pk_add_f32 v[2:3], v[2:3], v[126:127]
	v_mul_f32_e32 v4, 0xbfb8aa3b, v16
	v_mul_f32_e32 v14, 0xbfb8aa3b, v12
	v_exp_f32_e32 v14, v14
	v_exp_f32_e32 v15, v4
	s_waitcnt vmcnt(7)
	v_pk_mul_f32 v[0:1], v[0:1], v[128:129]
	v_pk_mul_f32 v[2:3], v[2:3], v[130:131]
	v_pk_add_f32 v[4:5], v[14:15], 1.0 op_sel_hi:[1,0]
	s_nop 0
	v_div_scale_f32 v8, s[4:5], v5, v5, v16
	v_rcp_f32_e32 v9, v8
	s_nop 0
	v_fma_f32 v14, -v8, v9, 1.0
	v_fmac_f32_e32 v9, v14, v9
	v_div_scale_f32 v14, vcc, v16, v5, v16
	v_mul_f32_e32 v15, v14, v9
	v_fma_f32 v17, -v8, v15, v14
	v_fmac_f32_e32 v15, v17, v9
	v_fma_f32 v8, -v8, v15, v14
	v_div_fmas_f32 v8, v8, v9, v15
	v_div_fixup_f32 v5, v8, v5, v16
	v_div_scale_f32 v8, s[4:5], v4, v4, v12
	v_rcp_f32_e32 v9, v8
	s_nop 0
	v_fma_f32 v14, -v8, v9, 1.0
	v_fmac_f32_e32 v9, v14, v9
	v_div_scale_f32 v14, vcc, v12, v4, v12
	v_mul_f32_e32 v15, v14, v9
	v_fma_f32 v16, -v8, v15, v14
	v_fmac_f32_e32 v15, v16, v9
	v_fma_f32 v8, -v8, v15, v14
	v_div_fmas_f32 v8, v8, v9, v15
	v_div_fixup_f32 v4, v8, v4, v12
	v_pk_mul_f32 v[0:1], v[0:1], v[4:5]
	v_cvt_f32_f16_e32 v8, v145
	v_cvt_pk_f16_f32 v0, v0, v1
	v_cvt_f32_f16_sdwa v1, v145 dst_sel:DWORD dst_unused:UNUSED_PAD src0_sel:WORD_1
	v_mul_f32_e32 v4, 0xbfb8aa3b, v8
	v_exp_f32_e32 v4, v4
	v_mul_f32_e32 v5, 0xbfb8aa3b, v1
	v_exp_f32_e32 v5, v5
	s_nop 0
	v_pk_add_f32 v[4:5], v[4:5], 1.0 op_sel_hi:[1,0]
	s_nop 0
	v_div_scale_f32 v6, s[4:5], v5, v5, v1
	v_rcp_f32_e32 v7, v6
	s_nop 0
	v_fma_f32 v9, -v6, v7, 1.0
	v_fmac_f32_e32 v7, v9, v7
	v_div_scale_f32 v9, vcc, v1, v5, v1
	v_mul_f32_e32 v10, v9, v7
	v_fma_f32 v11, -v6, v10, v9
	v_fmac_f32_e32 v10, v11, v7
	v_fma_f32 v6, -v6, v10, v9
	v_div_fmas_f32 v6, v6, v7, v10
	v_div_fixup_f32 v5, v6, v5, v1
	v_div_scale_f32 v1, s[4:5], v4, v4, v8
	v_rcp_f32_e32 v6, v1
	s_mov_b64 s[4:5], 0
	v_fma_f32 v7, -v1, v6, 1.0
	v_fmac_f32_e32 v6, v7, v6
	v_div_scale_f32 v7, vcc, v8, v4, v8
	v_mul_f32_e32 v9, v7, v6
	v_fma_f32 v10, -v1, v9, v7
	v_fmac_f32_e32 v9, v10, v6
	v_fma_f32 v1, -v1, v9, v7
	v_div_fmas_f32 v1, v1, v6, v9
	v_div_fixup_f32 v4, v1, v4, v8
	v_pk_mul_f32 v[2:3], v[2:3], v[4:5]
	s_nop 0
	v_cvt_pk_f16_f32 v1, v2, v3
	global_store_dwordx2 v[28:29], v[0:1], off offset:224
